# P6 K-loop: LDS-DMA pieces issued at the START of each load segment, before the ds_reads (pure intra-segment reorder); on top of v9
# baseline (speedup 1.0000x reference)
.LBB0_731:
	s_add_u32 s22, s0, 0xfff00080
	s_addc_u32 s23, s1, -1
	s_cmp_eq_u32 s61, 60
	s_cselect_b32 s25, s5, s23
	s_cselect_b32 s24, s57, s22
	s_cselect_b32 s23, s21, s60
	s_cselect_b32 s22, s58, s59
	v_lshl_add_u64 v[152:153], s[0:1], 0, v[140:141]
	s_add_i32 m0, s34, 0xc000
	s_nop 0
	global_load_lds_dwordx4 v[152:153], off
	v_lshl_add_u64 v[152:153], s[0:1], 0, v[142:143]
	s_add_i32 m0, s34, 0xe000
	s_nop 0
	global_load_lds_dwordx4 v[152:153], off
	ds_read_b128 v[148:151], v156
	ds_read_b128 v[160:163], v156 offset:1024
	ds_read_b128 v[164:167], v156 offset:2048
	ds_read_b128 v[168:171], v156 offset:3072
	ds_read_b128 v[176:179], v157
	ds_read_b128 v[180:183], v157 offset:1024
	ds_read_b128 v[184:187], v157 offset:2048
	ds_read_b128 v[188:191], v157 offset:3072
	ds_read_b128 v[192:195], v158
	ds_read_b128 v[196:199], v158 offset:1024
	ds_read_b128 v[200:203], v158 offset:2048
	ds_read_b128 v[204:207], v158 offset:3072
	ds_read_b128 v[208:211], v158 offset:4096
	ds_read_b128 v[212:215], v158 offset:5120
	ds_read_b128 v[216:219], v158 offset:6144
	ds_read_b128 v[220:223], v158 offset:7168
	s_waitcnt vmcnt(8)
	s_waitcnt lgkmcnt(0)
	s_barrier
	s_setprio 1
	s_waitcnt lgkmcnt(0)
	v_mfma_f32_16x16x32_bf16 v[126:129], v[148:151], v[192:195], v[126:129]
	v_mfma_f32_16x16x32_bf16 v[122:125], v[164:167], v[192:195], v[122:125]
	v_mfma_f32_16x16x32_bf16 v[110:113], v[148:151], v[200:203], v[110:113]
	v_mfma_f32_16x16x32_bf16 v[106:109], v[164:167], v[200:203], v[106:109]
	v_mfma_f32_16x16x32_bf16 v[94:97], v[148:151], v[208:211], v[94:97]
	v_mfma_f32_16x16x32_bf16 v[90:93], v[164:167], v[208:211], v[90:93]
	v_mfma_f32_16x16x32_bf16 v[78:81], v[148:151], v[216:219], v[78:81]
	v_mfma_f32_16x16x32_bf16 v[74:77], v[164:167], v[216:219], v[74:77]
	v_mfma_f32_16x16x32_bf16 v[126:129], v[160:163], v[196:199], v[126:129]
	v_mfma_f32_16x16x32_bf16 v[122:125], v[168:171], v[196:199], v[122:125]
	v_mfma_f32_16x16x32_bf16 v[110:113], v[160:163], v[204:207], v[110:113]
	v_mfma_f32_16x16x32_bf16 v[106:109], v[168:171], v[204:207], v[106:109]
	v_mfma_f32_16x16x32_bf16 v[94:97], v[160:163], v[212:215], v[94:97]
	v_mfma_f32_16x16x32_bf16 v[90:93], v[168:171], v[212:215], v[90:93]
	v_mfma_f32_16x16x32_bf16 v[78:81], v[160:163], v[220:223], v[78:81]
	v_mfma_f32_16x16x32_bf16 v[74:77], v[168:171], v[220:223], v[74:77]
	s_setprio 0
	s_setprio 1
	v_mfma_f32_16x16x32_bf16 v[118:121], v[176:179], v[192:195], v[118:121]
	v_mfma_f32_16x16x32_bf16 v[114:117], v[184:187], v[192:195], v[114:117]
	v_mfma_f32_16x16x32_bf16 v[102:105], v[176:179], v[200:203], v[102:105]
	v_mfma_f32_16x16x32_bf16 v[98:101], v[184:187], v[200:203], v[98:101]
	v_mfma_f32_16x16x32_bf16 v[86:89], v[176:179], v[208:211], v[86:89]
	v_mfma_f32_16x16x32_bf16 v[82:85], v[184:187], v[208:211], v[82:85]
	v_mfma_f32_16x16x32_bf16 v[70:73], v[176:179], v[216:219], v[70:73]
	v_mfma_f32_16x16x32_bf16 v[66:69], v[184:187], v[216:219], v[66:69]
	v_mfma_f32_16x16x32_bf16 v[118:121], v[180:183], v[196:199], v[118:121]
	v_mfma_f32_16x16x32_bf16 v[114:117], v[188:191], v[196:199], v[114:117]
	v_mfma_f32_16x16x32_bf16 v[102:105], v[180:183], v[204:207], v[102:105]
	v_mfma_f32_16x16x32_bf16 v[98:101], v[188:191], v[204:207], v[98:101]
	v_mfma_f32_16x16x32_bf16 v[86:89], v[180:183], v[212:215], v[86:89]
	v_mfma_f32_16x16x32_bf16 v[82:85], v[188:191], v[212:215], v[82:85]
	v_mfma_f32_16x16x32_bf16 v[70:73], v[180:183], v[220:223], v[70:73]
	v_mfma_f32_16x16x32_bf16 v[66:69], v[188:191], v[220:223], v[66:69]
	s_setprio 0
	s_barrier
	s_add_i32 s62, s44, s31
	v_lshl_add_u64 v[152:153], s[22:23], 0, v[136:137]
	s_mov_b32 m0, s62
	s_nop 0
	global_load_lds_dwordx4 v[152:153], off
	s_add_i32 m0, s62, 0x2000
	s_add_u32 s62, s22, 0x100000
	v_lshl_add_u64 v[172:173], s[22:23], 0, v[130:131]
	s_addc_u32 s63, s23, 0
	s_add_i32 s64, s45, s31
	global_load_lds_dwordx4 v[172:173], off
	v_lshl_add_u64 v[224:225], s[62:63], 0, v[136:137]
	s_mov_b32 m0, s64
	v_lshl_add_u64 v[226:227], s[24:25], 0, v[132:133]
	global_load_lds_dwordx4 v[224:225], off
	v_lshl_add_u64 v[224:225], s[62:63], 0, v[130:131]
	s_add_i32 m0, s64, 0x2000
	s_nop 0
	global_load_lds_dwordx4 v[224:225], off
	v_lshl_add_u64 v[224:225], s[24:25], 0, v[138:139]
	s_mov_b32 m0, s34
	s_nop 0
	global_load_lds_dwordx4 v[224:225], off
	s_mov_b32 m0, s35
	s_nop 0
	global_load_lds_dwordx4 v[226:227], off
	ds_read_b128 v[192:195], v158 offset:16384
	ds_read_b128 v[196:199], v158 offset:17408
	ds_read_b128 v[200:203], v158 offset:18432
	ds_read_b128 v[204:207], v158 offset:19456
	ds_read_b128 v[208:211], v158 offset:20480
	ds_read_b128 v[212:215], v158 offset:21504
	ds_read_b128 v[216:219], v158 offset:22528
	ds_read_b128 v[220:223], v158 offset:23552
	s_waitcnt vmcnt(8)
	s_waitcnt lgkmcnt(0)
	s_barrier
	s_setprio 1
	s_waitcnt lgkmcnt(0)
	v_mfma_f32_16x16x32_bf16 v[62:65], v[148:151], v[192:195], v[62:65]
	v_mfma_f32_16x16x32_bf16 v[58:61], v[164:167], v[192:195], v[58:61]
	v_mfma_f32_16x16x32_bf16 v[46:49], v[148:151], v[200:203], v[46:49]
	v_mfma_f32_16x16x32_bf16 v[42:45], v[164:167], v[200:203], v[42:45]
	v_mfma_f32_16x16x32_bf16 v[30:33], v[148:151], v[208:211], v[30:33]
	v_mfma_f32_16x16x32_bf16 v[26:29], v[164:167], v[208:211], v[26:29]
	v_mfma_f32_16x16x32_bf16 v[14:17], v[148:151], v[216:219], v[14:17]
	v_mfma_f32_16x16x32_bf16 v[10:13], v[164:167], v[216:219], v[10:13]
	v_mfma_f32_16x16x32_bf16 v[62:65], v[160:163], v[196:199], v[62:65]
	v_mfma_f32_16x16x32_bf16 v[58:61], v[168:171], v[196:199], v[58:61]
	v_mfma_f32_16x16x32_bf16 v[46:49], v[160:163], v[204:207], v[46:49]
	v_mfma_f32_16x16x32_bf16 v[42:45], v[168:171], v[204:207], v[42:45]
	v_mfma_f32_16x16x32_bf16 v[30:33], v[160:163], v[212:215], v[30:33]
	v_mfma_f32_16x16x32_bf16 v[26:29], v[168:171], v[212:215], v[26:29]
	v_mfma_f32_16x16x32_bf16 v[14:17], v[160:163], v[220:223], v[14:17]
	v_mfma_f32_16x16x32_bf16 v[10:13], v[168:171], v[220:223], v[10:13]
	s_setprio 0
	s_setprio 1
	v_mfma_f32_16x16x32_bf16 v[54:57], v[176:179], v[192:195], v[54:57]
	v_mfma_f32_16x16x32_bf16 v[50:53], v[184:187], v[192:195], v[50:53]
	v_mfma_f32_16x16x32_bf16 v[38:41], v[176:179], v[200:203], v[38:41]
	v_mfma_f32_16x16x32_bf16 v[34:37], v[184:187], v[200:203], v[34:37]
	v_mfma_f32_16x16x32_bf16 v[22:25], v[176:179], v[208:211], v[22:25]
	v_mfma_f32_16x16x32_bf16 v[18:21], v[184:187], v[208:211], v[18:21]
	v_mfma_f32_16x16x32_bf16 v[6:9], v[176:179], v[216:219], v[6:9]
	v_mfma_f32_16x16x32_bf16 v[2:5], v[184:187], v[216:219], v[2:5]
	v_mfma_f32_16x16x32_bf16 v[54:57], v[180:183], v[196:199], v[54:57]
	v_mfma_f32_16x16x32_bf16 v[50:53], v[188:191], v[196:199], v[50:53]
	v_mfma_f32_16x16x32_bf16 v[38:41], v[180:183], v[204:207], v[38:41]
	v_mfma_f32_16x16x32_bf16 v[34:37], v[188:191], v[204:207], v[34:37]
	v_mfma_f32_16x16x32_bf16 v[22:25], v[180:183], v[212:215], v[22:25]
	v_mfma_f32_16x16x32_bf16 v[18:21], v[188:191], v[212:215], v[18:21]
	v_mfma_f32_16x16x32_bf16 v[6:9], v[180:183], v[220:223], v[6:9]
	v_mfma_f32_16x16x32_bf16 v[2:5], v[188:191], v[220:223], v[2:5]
	s_setprio 0
	s_barrier
	s_add_u32 s24, s24, 0x100000
	s_addc_u32 s25, s25, 0
	s_mov_b32 m0, s36
	v_lshl_add_u64 v[228:229], s[24:25], 0, v[138:139]
	global_load_lds_dwordx4 v[228:229], off
	v_lshl_add_u64 v[228:229], s[24:25], 0, v[132:133]
	s_mov_b32 m0, s37
	s_nop 0
	global_load_lds_dwordx4 v[228:229], off
	s_add_i32 s62, 0, 0x18000
	v_add_u32_e32 v159, s62, v135
	s_add_i32 s63, 0, 0x1c000
	ds_read_b128 v[148:151], v159
	ds_read_b128 v[160:163], v159 offset:1024
	ds_read_b128 v[164:167], v159 offset:2048
	ds_read_b128 v[168:171], v159 offset:3072
	v_add_u32_e32 v159, s63, v135
	ds_read_b128 v[176:179], v159
	ds_read_b128 v[180:183], v159 offset:1024
	ds_read_b128 v[184:187], v159 offset:2048
	ds_read_b128 v[188:191], v159 offset:3072
	ds_read_b128 v[192:195], v158 offset:32768
	ds_read_b128 v[196:199], v158 offset:33792
	ds_read_b128 v[200:203], v158 offset:34816
	ds_read_b128 v[204:207], v158 offset:35840
	ds_read_b128 v[208:211], v158 offset:36864
	ds_read_b128 v[212:215], v158 offset:37888
	ds_read_b128 v[216:219], v158 offset:38912
	ds_read_b128 v[220:223], v158 offset:39936
	s_waitcnt vmcnt(8)
	s_waitcnt lgkmcnt(0)
	s_barrier
	s_setprio 1
	s_waitcnt lgkmcnt(0)
	v_mfma_f32_16x16x32_bf16 v[126:129], v[148:151], v[192:195], v[126:129]
	v_mfma_f32_16x16x32_bf16 v[122:125], v[164:167], v[192:195], v[122:125]
	v_mfma_f32_16x16x32_bf16 v[110:113], v[148:151], v[200:203], v[110:113]
	v_mfma_f32_16x16x32_bf16 v[106:109], v[164:167], v[200:203], v[106:109]
	v_mfma_f32_16x16x32_bf16 v[94:97], v[148:151], v[208:211], v[94:97]
	v_mfma_f32_16x16x32_bf16 v[90:93], v[164:167], v[208:211], v[90:93]
	v_mfma_f32_16x16x32_bf16 v[78:81], v[148:151], v[216:219], v[78:81]
	v_mfma_f32_16x16x32_bf16 v[74:77], v[164:167], v[216:219], v[74:77]
	v_mfma_f32_16x16x32_bf16 v[126:129], v[160:163], v[196:199], v[126:129]
	v_mfma_f32_16x16x32_bf16 v[122:125], v[168:171], v[196:199], v[122:125]
	v_mfma_f32_16x16x32_bf16 v[110:113], v[160:163], v[204:207], v[110:113]
	v_mfma_f32_16x16x32_bf16 v[106:109], v[168:171], v[204:207], v[106:109]
	v_mfma_f32_16x16x32_bf16 v[94:97], v[160:163], v[212:215], v[94:97]
	v_mfma_f32_16x16x32_bf16 v[90:93], v[168:171], v[212:215], v[90:93]
	v_mfma_f32_16x16x32_bf16 v[78:81], v[160:163], v[220:223], v[78:81]
	v_mfma_f32_16x16x32_bf16 v[74:77], v[168:171], v[220:223], v[74:77]
	s_setprio 0
	s_setprio 1
	v_mfma_f32_16x16x32_bf16 v[118:121], v[176:179], v[192:195], v[118:121]
	v_mfma_f32_16x16x32_bf16 v[114:117], v[184:187], v[192:195], v[114:117]
	v_mfma_f32_16x16x32_bf16 v[102:105], v[176:179], v[200:203], v[102:105]
	v_mfma_f32_16x16x32_bf16 v[98:101], v[184:187], v[200:203], v[98:101]
	v_mfma_f32_16x16x32_bf16 v[86:89], v[176:179], v[208:211], v[86:89]
	v_mfma_f32_16x16x32_bf16 v[82:85], v[184:187], v[208:211], v[82:85]
	v_mfma_f32_16x16x32_bf16 v[70:73], v[176:179], v[216:219], v[70:73]
	v_mfma_f32_16x16x32_bf16 v[66:69], v[184:187], v[216:219], v[66:69]
	v_mfma_f32_16x16x32_bf16 v[118:121], v[180:183], v[196:199], v[118:121]
	v_mfma_f32_16x16x32_bf16 v[114:117], v[188:191], v[196:199], v[114:117]
	v_mfma_f32_16x16x32_bf16 v[102:105], v[180:183], v[204:207], v[102:105]
	v_mfma_f32_16x16x32_bf16 v[98:101], v[188:191], v[204:207], v[98:101]
	v_mfma_f32_16x16x32_bf16 v[86:89], v[180:183], v[212:215], v[86:89]
	v_mfma_f32_16x16x32_bf16 v[82:85], v[188:191], v[212:215], v[82:85]
	v_mfma_f32_16x16x32_bf16 v[70:73], v[180:183], v[220:223], v[70:73]
	v_mfma_f32_16x16x32_bf16 v[66:69], v[188:191], v[220:223], v[66:69]
	s_setprio 0
	s_barrier
	s_add_i32 s24, s62, s31
	v_lshl_add_u64 v[152:153], v[152:153], 0, s[16:17]
	s_mov_b32 m0, s24
	s_nop 0
	global_load_lds_dwordx4 v[152:153], off
	s_add_i32 m0, s24, 0x2000
	s_add_u32 s22, s22, 0x100080
	v_lshl_add_u64 v[152:153], v[172:173], 0, s[16:17]
	s_addc_u32 s23, s23, 0
	s_add_i32 s24, s63, s31
	global_load_lds_dwordx4 v[152:153], off
	v_lshl_add_u64 v[152:153], s[22:23], 0, v[136:137]
	s_mov_b32 m0, s24
	s_nop 0
	global_load_lds_dwordx4 v[152:153], off
	v_lshl_add_u64 v[152:153], s[22:23], 0, v[130:131]
	s_add_i32 m0, s24, 0x2000
	s_nop 0
	global_load_lds_dwordx4 v[152:153], off
	v_lshl_add_u64 v[152:153], v[224:225], 0, s[16:17]
	s_mov_b32 m0, s40
	s_nop 0
	global_load_lds_dwordx4 v[152:153], off
	v_lshl_add_u64 v[152:153], v[226:227], 0, s[16:17]
	s_mov_b32 m0, s41
	s_nop 0
	global_load_lds_dwordx4 v[152:153], off
	ds_read_b128 v[192:195], v158 offset:49152
	ds_read_b128 v[196:199], v158 offset:50176
	ds_read_b128 v[200:203], v158 offset:51200
	ds_read_b128 v[204:207], v158 offset:52224
	ds_read_b128 v[208:211], v158 offset:53248
	ds_read_b128 v[212:215], v158 offset:54272
	ds_read_b128 v[216:219], v158 offset:55296
	ds_read_b128 v[220:223], v158 offset:56320
	s_waitcnt vmcnt(8)
	s_waitcnt lgkmcnt(0)
	s_barrier
	s_setprio 1
	s_waitcnt lgkmcnt(0)
	v_mfma_f32_16x16x32_bf16 v[62:65], v[148:151], v[192:195], v[62:65]
	v_mfma_f32_16x16x32_bf16 v[58:61], v[164:167], v[192:195], v[58:61]
	v_mfma_f32_16x16x32_bf16 v[46:49], v[148:151], v[200:203], v[46:49]
	v_mfma_f32_16x16x32_bf16 v[42:45], v[164:167], v[200:203], v[42:45]
	v_mfma_f32_16x16x32_bf16 v[30:33], v[148:151], v[208:211], v[30:33]
	v_mfma_f32_16x16x32_bf16 v[26:29], v[164:167], v[208:211], v[26:29]
	v_mfma_f32_16x16x32_bf16 v[14:17], v[148:151], v[216:219], v[14:17]
	v_mfma_f32_16x16x32_bf16 v[10:13], v[164:167], v[216:219], v[10:13]
	v_mfma_f32_16x16x32_bf16 v[62:65], v[160:163], v[196:199], v[62:65]
	v_mfma_f32_16x16x32_bf16 v[58:61], v[168:171], v[196:199], v[58:61]
	v_mfma_f32_16x16x32_bf16 v[46:49], v[160:163], v[204:207], v[46:49]
	v_mfma_f32_16x16x32_bf16 v[42:45], v[168:171], v[204:207], v[42:45]
	v_mfma_f32_16x16x32_bf16 v[30:33], v[160:163], v[212:215], v[30:33]
	v_mfma_f32_16x16x32_bf16 v[26:29], v[168:171], v[212:215], v[26:29]
	v_mfma_f32_16x16x32_bf16 v[14:17], v[160:163], v[220:223], v[14:17]
	v_mfma_f32_16x16x32_bf16 v[10:13], v[168:171], v[220:223], v[10:13]
	s_setprio 0
	s_setprio 1
	v_mfma_f32_16x16x32_bf16 v[54:57], v[176:179], v[192:195], v[54:57]
	v_mfma_f32_16x16x32_bf16 v[50:53], v[184:187], v[192:195], v[50:53]
	v_mfma_f32_16x16x32_bf16 v[38:41], v[176:179], v[200:203], v[38:41]
	v_mfma_f32_16x16x32_bf16 v[34:37], v[184:187], v[200:203], v[34:37]
	v_mfma_f32_16x16x32_bf16 v[22:25], v[176:179], v[208:211], v[22:25]
	v_mfma_f32_16x16x32_bf16 v[18:21], v[184:187], v[208:211], v[18:21]
	v_mfma_f32_16x16x32_bf16 v[6:9], v[176:179], v[216:219], v[6:9]
	v_mfma_f32_16x16x32_bf16 v[2:5], v[184:187], v[216:219], v[2:5]
	v_mfma_f32_16x16x32_bf16 v[54:57], v[180:183], v[196:199], v[54:57]
	v_mfma_f32_16x16x32_bf16 v[50:53], v[188:191], v[196:199], v[50:53]
	v_mfma_f32_16x16x32_bf16 v[38:41], v[180:183], v[204:207], v[38:41]
	v_mfma_f32_16x16x32_bf16 v[34:37], v[188:191], v[204:207], v[34:37]
	v_mfma_f32_16x16x32_bf16 v[22:25], v[180:183], v[212:215], v[22:25]
	v_mfma_f32_16x16x32_bf16 v[18:21], v[188:191], v[212:215], v[18:21]
	v_mfma_f32_16x16x32_bf16 v[6:9], v[180:183], v[220:223], v[6:9]
	v_mfma_f32_16x16x32_bf16 v[2:5], v[188:191], v[220:223], v[2:5]
	s_setprio 0
	s_barrier
	s_add_i32 s61, s61, 2
	s_add_u32 s0, s0, 0x100
	s_addc_u32 s1, s1, 0
	s_add_u32 s59, s59, 0x100
	s_addc_u32 s60, s60, 0
	s_cmp_gt_u32 s61, 61
	s_cbranch_scc0 .LBB0_731
	v_and_b32_e32 v165, 3, v174
	v_lshrrev_b32_e32 v170, 2, v174
	v_lshlrev_b32_e32 v164, 6, v165
	v_and_or_b32 v164, v174, 60, v164
	v_and_b32_e32 v171, 15, v174
	v_sub_u32_e32 v170, v170, v171
	v_lshrrev_b32_e32 v171, 4, v174
	v_sub_u32_e32 v165, v165, v171
	v_mul_i32_i24_e32 v170, 0xac00, v170
	v_lshl_add_u32 v166, v165, 4, v170
	v_ashrrev_i32_e32 v167, 31, v166
	s_lshl_b32 s5, s56, 8
	s_add_i32 s5, s5, s39
	v_or_b32_e32 v159, s5, v1
	v_cmp_lt_i32_e64 s[0:1], s46, v159
	s_and_b64 s[22:23], s[0:1], s[18:19]
	v_mov_b64_e32 v[150:151], 0
	s_and_saveexec_b64 s[0:1], s[22:23]
	v_add_u32_e32 v148, 0xffffe000, v159
	v_lshrrev_b32_e32 v148, 2, v148
	v_and_b32_e32 v148, 0x3ffffff2, v148
	v_add_u32_e32 v150, v148, v154
	v_mov_b64_e32 v[148:149], s[10:11]
	v_mad_u64_u32 v[150:151], s[22:23], v150, s47, v[148:149]
	s_or_b64 exec, exec, s[0:1]
	v_lshl_or_b32 v148, s55, 8, v155
	v_mov_b64_e32 v[152:153], s[6:7]
	v_ashrrev_i32_e32 v149, 31, v148
	v_mad_i64_i32 v[152:153], s[0:1], v159, s48, v[152:153]
	v_lshl_add_u64 v[152:153], v[148:149], 1, v[152:153]
	v_cmp_ne_u64_e64 s[0:1], 0, v[150:151]
	v_lshl_add_u64 v[150:151], v[148:149], 2, v[150:151]
	v_cvt_pk_bf16_f32 v160, v126, v127
	v_cvt_pk_bf16_f32 v161, v128, v129
	v_cvt_pk_bf16_f32 v162, v122, v123
	v_cvt_pk_bf16_f32 v163, v124, v125
	ds_bpermute_b32 v160, v164, v160
	ds_bpermute_b32 v161, v164, v161
	ds_bpermute_b32 v162, v164, v162
	ds_bpermute_b32 v163, v164, v163
	v_lshl_add_u64 v[168:169], v[166:167], 0, v[152:153]
	s_waitcnt lgkmcnt(0)
	global_store_dwordx4 v[168:169], v[160:163], off
	s_and_saveexec_b64 s[22:23], s[0:1]
	s_cbranch_execz .LBB0_736
	global_store_dwordx4 v[150:151], v[126:129], off
	global_store_dwordx4 v[150:151], v[122:125], off offset:16
